# attention: next key block K rows prefetched one iteration ahead, on top of the blocked V^T version
# baseline (speedup 1.0000x reference)
.LBB0_842:
	s_or_b64 exec, exec, s[10:11]
	v_readfirstlane_b32 s12, v0
	s_cmpk_gt_i32 s12, 0xfff
	s_mov_b64 s[10:11], -1
	s_cbranch_scc1 .LBB0_837
	s_ashr_i32 s14, s12, 9
	s_lshl_b32 s16, s12, 4
	s_and_b32 s11, s16, 0x7f0
	s_ashr_i32 s15, s14, 31
	s_ashr_i32 s10, s12, 7
	s_lshl_b64 s[12:13], s[14:15], 11
	v_or_b32_e32 v33, s11, v32
	v_or_b32_e32 v42, s12, v33
	v_mov_b64_e32 v[0:1], s[20:21]
	s_lshl_b32 s11, s10, 6
	v_mad_u64_u32 v[0:1], s[14:15], v42, s90, v[0:1]
	s_and_b32 s46, s11, 0xc0
	v_mad_i32_i24 v1, s13, v222, v1
	s_lshl_b32 s44, s46, 1
	v_lshl_add_u64 v[0:1], v[0:1], 0, s[44:45]
	v_lshlrev_b32_e32 v156, 1, v34
	v_lshl_add_u64 v[0:1], v[0:1], 0, v[156:157]
	global_load_dwordx4 v[16:19], v[0:1], off
	global_load_dwordx4 v[20:23], v[0:1], off offset:64
	v_and_b32_e32 v0, 63, v217
	v_cmp_gt_u32_e32 vcc, 48, v0
	s_ashr_i32 s11, s10, 31
	s_lshl_b64 s[10:11], s[10:11], 18
	v_cndmask_b32_e64 v1, 0, 16, vcc
	v_cmp_gt_u32_e32 vcc, 16, v0
	v_mov_b32_e32 v28, 0
	v_mov_b32_e32 v43, s13
	v_cndmask_b32_e64 v0, 0, 48, vcc
	v_add_lshl_u32 v50, v0, v217, 2
	v_and_or_b32 v0, v217, 64, v32
	v_mov_b32_e32 v45, s13
	v_or_b32_e32 v44, s12, v32
	v_add_lshl_u32 v35, v1, v217, 2
	v_lshl_or_b32 v37, v217, 2, v223
	v_lshlrev_b32_e32 v51, 2, v0
	v_lshl_add_u64 v[46:47], v[38:39], 0, s[10:11]
	s_and_b32 s58, s16, 0x7e0
	v_mov_b32_e32 v0, 0
	v_mov_b32_e32 v1, v28
	v_mov_b32_e32 v2, v28
	v_mov_b32_e32 v3, v28
	v_mov_b32_e32 v4, 0
	v_mov_b32_e32 v5, v28
	v_mov_b32_e32 v6, v28
	v_mov_b32_e32 v7, v28
	v_mov_b32_e32 v8, 0
	v_mov_b32_e32 v9, v28
	v_mov_b32_e32 v10, v28
	v_mov_b32_e32 v11, v28
	v_mov_b32_e32 v12, 0
	v_mov_b32_e32 v13, v28
	v_mov_b32_e32 v14, v28
	v_mov_b32_e32 v15, v28
	v_mov_b32_e32 v144, 0x3c000
	s_mov_b32 s59, s45
	v_lshl_add_u64 v[142:143], v[44:45], 0, s[58:59]
	v_mov_b64_e32 v[140:141], s[20:21]
	v_mad_u64_u32 v[140:141], s[10:11], v142, s90, v[140:141]
	v_mad_i32_i24 v141, v143, s90, v141
	s_lshl_b32 s44, s46, 1
	v_lshl_add_u64 v[140:141], v[140:141], 0, s[44:45]
	v_lshl_add_u64 v[140:141], v[140:141], 0, v[156:157]
	v_add_co_u32_e32 v142, vcc, s76, v140
	s_mov_b64 s[10:11], 0x1e200
	s_nop 0
	v_addc_co_u32_e32 v143, vcc, 0, v141, vcc
	global_load_dwordx4 v[120:123], v[142:143], off offset:512
	v_lshl_add_u64 v[142:143], v[140:141], 0, s[10:11]
	global_load_dwordx4 v[124:127], v[142:143], off offset:64
	global_load_dwordx4 v[128:131], v[140:141], off offset:512
	global_load_dwordx4 v[132:135], v[140:141], off offset:576
.LBB0_844:
	s_mov_b32 s59, s45
	s_lshl_b32 s10, s58, 7
	s_mov_b32 s11, 0
	v_lshl_add_u64 v[116:117], v[46:47], 0, s[10:11]
	s_waitcnt vmcnt(0)
	v_mfma_f32_16x16x32_bf16 v[24:27], v[120:123], v[16:19], 0
	v_mfma_f32_16x16x32_bf16 v[136:139], v[128:131], v[16:19], 0
	v_mfma_f32_16x16x32_bf16 v[24:27], v[124:127], v[20:23], v[24:27]
	v_mfma_f32_16x16x32_bf16 v[136:139], v[132:135], v[20:23], v[136:139]
	global_load_dwordx2 v[100:101], v[116:117], off
	global_load_dwordx2 v[102:103], v[116:117], off offset:32
	global_load_dwordx2 v[104:105], v[116:117], off offset:1024
	global_load_dwordx2 v[106:107], v[116:117], off offset:1056
	global_load_dwordx2 v[108:109], v[116:117], off offset:2048
	global_load_dwordx2 v[110:111], v[116:117], off offset:2080
	global_load_dwordx2 v[112:113], v[116:117], off offset:3072
	global_load_dwordx2 v[114:115], v[116:117], off offset:3104
	v_sub_co_u32_e32 v140, vcc, v140, v144
	s_nop 1
	v_subbrev_co_u32_e32 v141, vcc, 0, v141, vcc
	v_add_co_u32_e32 v142, vcc, s76, v140
	s_mov_b64 s[10:11], 0x1e200
	s_nop 0
	v_addc_co_u32_e32 v143, vcc, 0, v141, vcc
	global_load_dwordx4 v[120:123], v[142:143], off offset:512
	v_lshl_add_u64 v[142:143], v[140:141], 0, s[10:11]
	global_load_dwordx4 v[124:127], v[142:143], off offset:64
	global_load_dwordx4 v[128:131], v[140:141], off offset:512
	global_load_dwordx4 v[132:135], v[140:141], off offset:576
	v_add_u32_e32 v29, s58, v36
	v_add_u32_e32 v30, 16, v29
	v_cmp_lt_u32_e32 vcc, v30, v33
	s_nop 7
	v_mul_f32_e32 v31, 0x3e000000, v24
	v_max_f32_e32 v30, 0, v31
	v_mul_f32_e64 v31, |v31|, s83
	v_exp_f32_e32 v31, v31
	s_nop 0
	v_add_f32_e32 v31, 1.0, v31
	v_cmp_gt_f32_e64 s[10:11], s93, v31
	s_nop 1
	v_cndmask_b32_e64 v52, 0, 32, s[10:11]
	v_ldexp_f32 v31, v31, v52
	v_log_f32_e32 v31, v31
	s_nop 0
	v_mul_f32_e32 v52, 0x3f317217, v31
	v_fma_f32 v52, v31, s96, -v52
	v_fmac_f32_e32 v52, 0x3377d1cf, v31
	v_fmac_f32_e32 v52, 0x3f317217, v31
	v_cmp_lt_f32_e64 s[12:13], |v31|, s77
	s_nop 1
	v_cndmask_b32_e64 v31, v31, v52, s[12:13]
	v_cndmask_b32_e64 v52, 0, v224, s[10:11]
	v_sub_f32_e32 v31, v31, v52
	v_add_f32_e32 v30, v30, v31
	v_cndmask_b32_e64 v31, 0, -v30, vcc
	v_fma_f32 v24, v24, s97, -v30
	v_mul_f32_e32 v30, 0x3e000000, v25
	v_add_u32_e32 v52, 17, v29
	v_cmp_lt_u32_e64 s[10:11], v52, v33
	v_max_f32_e32 v52, 0, v30
	v_mul_f32_e64 v30, |v30|, s83
	v_exp_f32_e32 v30, v30
	s_nop 0
	v_add_f32_e32 v30, 1.0, v30
	v_cmp_gt_f32_e64 s[12:13], s93, v30
	s_nop 1
	v_cndmask_b32_e64 v53, 0, 32, s[12:13]
	v_ldexp_f32 v30, v30, v53
	v_log_f32_e32 v30, v30
	s_nop 0
	v_mul_f32_e32 v53, 0x3f317217, v30
	v_fma_f32 v53, v30, s96, -v53
	v_fmac_f32_e32 v53, 0x3377d1cf, v30
	v_fmac_f32_e32 v53, 0x3f317217, v30
	v_cmp_lt_f32_e64 s[14:15], |v30|, s77
	s_nop 1
	v_cndmask_b32_e64 v30, v30, v53, s[14:15]
	v_cndmask_b32_e64 v53, 0, v224, s[12:13]
	v_sub_f32_e32 v30, v30, v53
	v_add_f32_e32 v30, v52, v30
	v_cndmask_b32_e64 v52, 0, -v30, s[10:11]
	v_fma_f32 v25, v25, s97, -v30
	v_mul_f32_e32 v30, 0x3e000000, v26
	v_add_u32_e32 v53, 18, v29
	v_cmp_lt_u32_e64 s[12:13], v53, v33
	v_max_f32_e32 v53, 0, v30
	v_mul_f32_e64 v30, |v30|, s83
	v_exp_f32_e32 v30, v30
	s_nop 0
	v_add_f32_e32 v30, 1.0, v30
	v_cmp_gt_f32_e64 s[14:15], s93, v30
	s_nop 1
	v_cndmask_b32_e64 v54, 0, 32, s[14:15]
	v_ldexp_f32 v30, v30, v54
	v_log_f32_e32 v30, v30
	s_nop 0
	v_mul_f32_e32 v54, 0x3f317217, v30
	v_fma_f32 v54, v30, s96, -v54
	v_fmac_f32_e32 v54, 0x3377d1cf, v30
	v_fmac_f32_e32 v54, 0x3f317217, v30
	v_cmp_lt_f32_e64 s[16:17], |v30|, s77
	s_nop 1
	v_cndmask_b32_e64 v30, v30, v54, s[16:17]
	v_cndmask_b32_e64 v54, 0, v224, s[14:15]
	v_sub_f32_e32 v30, v30, v54
	v_add_f32_e32 v30, v53, v30
	v_cndmask_b32_e64 v53, 0, -v30, s[12:13]
	v_fma_f32 v26, v26, s97, -v30
	v_mul_f32_e32 v30, 0x3e000000, v27
	v_add_u32_e32 v54, 19, v29
	v_cmp_lt_u32_e64 s[14:15], v54, v33
	v_max_f32_e32 v54, 0, v30
	v_mul_f32_e64 v30, |v30|, s83
	v_exp_f32_e32 v30, v30
	s_nop 0
	v_add_f32_e32 v30, 1.0, v30
	v_cmp_gt_f32_e64 s[16:17], s93, v30
	s_nop 1
	v_cndmask_b32_e64 v55, 0, 32, s[16:17]
	v_ldexp_f32 v30, v30, v55
	v_log_f32_e32 v30, v30
	s_nop 0
	v_mul_f32_e32 v55, 0x3f317217, v30
	v_fma_f32 v55, v30, s96, -v55
	v_fmac_f32_e32 v55, 0x3377d1cf, v30
	v_fmac_f32_e32 v55, 0x3f317217, v30
	v_cmp_lt_f32_e64 s[18:19], |v30|, s77
	s_nop 1
	v_cndmask_b32_e64 v30, v30, v55, s[18:19]
	v_cndmask_b32_e64 v55, 0, v224, s[16:17]
	v_sub_f32_e32 v30, v30, v55
	v_add_f32_e32 v30, v54, v30
	v_cndmask_b32_e64 v55, 0, -v30, s[14:15]
	v_add_f32_e32 v54, v55, v53
	v_add_f32_e32 v52, v52, v54
	v_fma_f32 v27, v27, s97, -v30
	v_add_f32_e32 v30, v31, v52
	ds_bpermute_b32 v31, v35, v30
	ds_bpermute_b32 v53, v37, v30
	ds_bpermute_b32 v56, v50, v30
	s_waitcnt lgkmcnt(2)
	v_cndmask_b32_e64 v31, v31, 0, s[4:5]
	s_waitcnt lgkmcnt(1)
	v_cndmask_b32_e64 v53, 0, v53, s[6:7]
	v_add_f32_e32 v31, v31, v53
	s_waitcnt lgkmcnt(0)
	v_cndmask_b32_e64 v53, 0, v56, s[8:9]
	v_add_f32_e32 v31, v31, v53
	v_add_f32_e32 v30, v31, v30
	v_add_f32_e32 v31, v28, v31
	v_add_f32_e32 v24, v31, v24
	v_add_f32_e32 v24, v24, v52
	v_mul_f32_e32 v24, 0x3fb8aa3b, v24
	v_exp_f32_e32 v24, v24
	ds_bpermute_b32 v30, v51, v30
	v_cndmask_b32_e32 v53, 0, v24, vcc
	v_add_f32_e32 v24, v31, v25
	v_add_f32_e32 v24, v54, v24
	v_mul_f32_e32 v24, 0x3fb8aa3b, v24
	v_exp_f32_e32 v24, v24
	v_cmp_lt_u32_e32 vcc, v29, v33
	v_cndmask_b32_e64 v54, 0, v24, s[10:11]
	v_add_f32_e32 v24, v31, v26
	v_add_f32_e32 v24, v55, v24
	v_mul_f32_e32 v24, 0x3fb8aa3b, v24
	v_exp_f32_e32 v24, v24
	s_nop 0
	v_cndmask_b32_e64 v55, 0, v24, s[12:13]
	v_add_f32_e32 v24, v31, v27
	v_mul_f32_e32 v24, 0x3fb8aa3b, v24
	v_exp_f32_e32 v24, v24
	s_nop 0
	v_cndmask_b32_e64 v56, 0, v24, s[14:15]
	v_mov_b32_e32 v24, v136
	v_mov_b32_e32 v25, v137
	v_mov_b32_e32 v26, v138
	v_mov_b32_e32 v27, v139
	v_mul_f32_e32 v31, 0x3e000000, v24
	v_max_f32_e32 v48, 0, v31
	v_mul_f32_e64 v31, |v31|, s83
	v_exp_f32_e32 v31, v31
	s_nop 0
	v_add_f32_e32 v31, 1.0, v31
	v_cmp_gt_f32_e64 s[10:11], s93, v31
	s_nop 1
	v_cndmask_b32_e64 v49, 0, 32, s[10:11]
	v_ldexp_f32 v31, v31, v49
	v_log_f32_e32 v31, v31
	s_nop 0
	v_mul_f32_e32 v49, 0x3f317217, v31
	v_fma_f32 v49, v31, s96, -v49
	v_fmac_f32_e32 v49, 0x3377d1cf, v31
	v_fmac_f32_e32 v49, 0x3f317217, v31
	v_cmp_lt_f32_e64 s[12:13], |v31|, s77
	s_nop 1
	v_cndmask_b32_e64 v31, v31, v49, s[12:13]
	v_cndmask_b32_e64 v49, 0, v224, s[10:11]
	v_sub_f32_e32 v31, v31, v49
	v_add_f32_e32 v48, v48, v31
	v_cndmask_b32_e64 v31, 0, -v48, vcc
	v_fma_f32 v24, v24, s97, -v48
	v_mul_f32_e32 v48, 0x3e000000, v25
	v_add_u32_e32 v49, 1, v29
	v_cmp_lt_u32_e64 s[10:11], v49, v33
	v_max_f32_e32 v49, 0, v48
	v_mul_f32_e64 v48, |v48|, s83
	v_exp_f32_e32 v48, v48
	s_nop 0
	v_add_f32_e32 v48, 1.0, v48
	v_cmp_gt_f32_e64 s[12:13], s93, v48
	s_nop 1
	v_cndmask_b32_e64 v52, 0, 32, s[12:13]
	v_ldexp_f32 v48, v48, v52
	v_log_f32_e32 v48, v48
	s_nop 0
	v_mul_f32_e32 v52, 0x3f317217, v48
	v_fma_f32 v52, v48, s96, -v52
	v_fmac_f32_e32 v52, 0x3377d1cf, v48
	v_fmac_f32_e32 v52, 0x3f317217, v48
	v_cmp_lt_f32_e64 s[14:15], |v48|, s77
	s_nop 1
	v_cndmask_b32_e64 v48, v48, v52, s[14:15]
	v_cndmask_b32_e64 v52, 0, v224, s[12:13]
	v_sub_f32_e32 v48, v48, v52
	v_add_f32_e32 v48, v49, v48
	v_cndmask_b32_e64 v49, 0, -v48, s[10:11]
	v_fma_f32 v25, v25, s97, -v48
	v_mul_f32_e32 v48, 0x3e000000, v26
	v_add_u32_e32 v52, 2, v29
	v_cmp_lt_u32_e64 s[12:13], v52, v33
	v_max_f32_e32 v52, 0, v48
	v_mul_f32_e64 v48, |v48|, s83
	v_exp_f32_e32 v48, v48
	v_add_u32_e32 v29, 3, v29
	v_add_f32_e32 v48, 1.0, v48
	v_cmp_gt_f32_e64 s[14:15], s93, v48
	s_nop 1
	v_cndmask_b32_e64 v57, 0, 32, s[14:15]
	v_ldexp_f32 v48, v48, v57
	v_log_f32_e32 v48, v48
	s_nop 0
	v_mul_f32_e32 v57, 0x3f317217, v48
	v_fma_f32 v57, v48, s96, -v57
	v_fmac_f32_e32 v57, 0x3377d1cf, v48
	v_fmac_f32_e32 v57, 0x3f317217, v48
	v_cmp_lt_f32_e64 s[16:17], |v48|, s77
	s_nop 1
	v_cndmask_b32_e64 v48, v48, v57, s[16:17]
	v_cndmask_b32_e64 v57, 0, v224, s[14:15]
	v_sub_f32_e32 v48, v48, v57
	v_add_f32_e32 v48, v52, v48
	v_cndmask_b32_e64 v52, 0, -v48, s[12:13]
	v_fma_f32 v26, v26, s97, -v48
	v_mul_f32_e32 v48, 0x3e000000, v27
	v_cmp_lt_u32_e64 s[14:15], v29, v33
	v_max_f32_e32 v29, 0, v48
	v_mul_f32_e64 v48, |v48|, s83
	v_exp_f32_e32 v48, v48
	s_nop 0
	v_add_f32_e32 v48, 1.0, v48
	v_cmp_gt_f32_e64 s[16:17], s93, v48
	s_nop 1
	v_cndmask_b32_e64 v57, 0, 32, s[16:17]
	v_ldexp_f32 v48, v48, v57
	v_log_f32_e32 v48, v48
	s_nop 0
	v_mul_f32_e32 v57, 0x3f317217, v48
	v_fma_f32 v57, v48, s96, -v57
	v_fmac_f32_e32 v57, 0x3377d1cf, v48
	v_fmac_f32_e32 v57, 0x3f317217, v48
	v_cmp_lt_f32_e64 s[18:19], |v48|, s77
	s_nop 1
	v_cndmask_b32_e64 v48, v48, v57, s[18:19]
	v_cndmask_b32_e64 v57, 0, v224, s[16:17]
	v_sub_f32_e32 v48, v48, v57
	v_add_f32_e32 v29, v29, v48
	v_cndmask_b32_e64 v57, 0, -v29, s[14:15]
	v_add_f32_e32 v58, v57, v52
	v_add_f32_e32 v59, v49, v58
	v_add_f32_e32 v52, v31, v59
	v_fma_f32 v27, v27, s97, -v29
	ds_bpermute_b32 v29, v35, v52
	ds_bpermute_b32 v31, v37, v52
	ds_bpermute_b32 v48, v50, v52
	s_waitcnt lgkmcnt(2)
	v_cndmask_b32_e64 v29, v29, 0, s[4:5]
	s_waitcnt lgkmcnt(1)
	v_cndmask_b32_e64 v31, 0, v31, s[6:7]
	v_add_f32_e32 v29, v29, v31
	s_waitcnt lgkmcnt(0)
	v_cndmask_b32_e64 v31, 0, v48, s[8:9]
	v_pk_add_f32 v[48:49], v[28:29], v[30:31]
	s_nop 0
	v_add_f32_e32 v28, v49, v52
	ds_bpermute_b32 v52, v51, v28
	v_add_f32_e32 v28, v48, v49
	v_add_f32_e32 v24, v28, v24
	v_add_f32_e32 v25, v28, v25
	v_add_f32_e32 v26, v28, v26
	v_add_f32_e32 v24, v24, v59
	v_add_f32_e32 v25, v58, v25
	v_add_f32_e32 v26, v57, v26
	v_add_f32_e32 v27, v28, v27
	v_mul_f32_e32 v24, 0x3fb8aa3b, v24
	v_mul_f32_e32 v25, 0x3fb8aa3b, v25
	v_mul_f32_e32 v26, 0x3fb8aa3b, v26
	v_mul_f32_e32 v27, 0x3fb8aa3b, v27
	v_exp_f32_e32 v24, v24
	v_exp_f32_e32 v25, v25
	v_exp_f32_e32 v26, v26
	v_exp_f32_e32 v27, v27
	v_cndmask_b32_e32 v24, 0, v24, vcc
	v_cndmask_b32_e64 v25, 0, v25, s[10:11]
	v_cndmask_b32_e64 v26, 0, v26, s[12:13]
	v_cndmask_b32_e64 v27, 0, v27, s[14:15]
	v_cvt_pk_bf16_f32 v24, v24, v25
	v_cvt_pk_bf16_f32 v25, v26, v27
	v_cvt_pk_bf16_f32 v26, v53, v54
	v_cvt_pk_bf16_f32 v27, v55, v56
	s_mov_b32 s10, 0xc2b40000
	s_nop 1
	s_waitcnt vmcnt(10)
	v_mfma_f32_16x16x32_bf16 v[12:15], v[100:103], v[24:27], v[12:15]
	s_waitcnt vmcnt(8)
	v_mfma_f32_16x16x32_bf16 v[8:11], v[104:107], v[24:27], v[8:11]
	s_waitcnt vmcnt(6)
	v_mfma_f32_16x16x32_bf16 v[4:7], v[108:111], v[24:27], v[4:7]
	s_waitcnt vmcnt(4)
	v_mfma_f32_16x16x32_bf16 v[0:3], v[112:115], v[24:27], v[0:3]
	s_waitcnt lgkmcnt(0)
	v_add_f32_e32 v28, v48, v52
	v_cmp_gt_f32_e32 vcc, s10, v28
	s_cmp_lg_u64 vcc, exec
	s_cselect_b64 s[10:11], -1, 0
	s_cmp_lg_u32 s58, 0
	s_cselect_b64 s[12:13], -1, 0
	s_and_b64 s[10:11], s[12:13], s[10:11]
	s_sub_i32 s58, s58, 32
	s_and_b64 vcc, exec, s[10:11]
	s_cbranch_vccnz .LBB0_844
	v_pk_mul_f32 v[16:17], v[14:15], v[14:15]
	v_pk_mul_f32 v[18:19], v[12:13], v[12:13]
	v_lshlrev_b32_e32 v156, 1, v36
	v_pk_mov_b32 v[20:21], v[18:19], v[16:17] op_sel:[1,0]
	v_mov_b32_e32 v19, v17
	v_pk_add_f32 v[16:17], v[20:21], v[18:19]
	v_pk_mul_f32 v[18:19], v[10:11], v[10:11]
	v_pk_mul_f32 v[20:21], v[8:9], v[8:9]
	v_pk_add_f32 v[16:17], v[16:17], v[16:17] op_sel:[0,1] op_sel_hi:[1,0]
	v_pk_mov_b32 v[22:23], v[20:21], v[18:19] op_sel:[1,0]
	v_mov_b32_e32 v21, v19
	v_pk_add_f32 v[18:19], v[22:23], v[20:21]
	v_mul_f32_e32 v20, v0, v0
	v_mul_f32_e32 v21, v1, v1
	v_pk_add_f32 v[18:19], v[18:19], v[18:19] op_sel:[0,1] op_sel_hi:[1,0]
	v_mov_b32_e32 v17, v20
	v_mov_b32_e32 v19, v21
	v_pk_add_f32 v[16:17], v[16:17], v[18:19]
	v_mul_f32_e32 v18, v5, v5
	v_mul_f32_e32 v20, v7, v7
	v_mul_f32_e32 v22, v2, v2
	v_mul_f32_e32 v23, v3, v3
	v_pk_fma_f32 v[18:19], v[4:5], v[4:5], v[18:19] op_sel_hi:[1,1,0]
	v_pk_fma_f32 v[20:21], v[6:7], v[6:7], v[20:21] op_sel_hi:[1,1,0]
	v_mov_b32_e32 v19, v22
	v_mov_b32_e32 v21, v23
	v_pk_add_f32 v[18:19], v[18:19], v[20:21]
	global_load_dwordx4 v[20:23], v[40:41], off
	v_pk_add_f32 v[16:17], v[16:17], v[18:19]
	v_and_b32_e32 v18, 64, v217
	v_add_f32_e32 v16, v16, v17
	v_xor_b32_e32 v17, 16, v217
	v_add_u32_e32 v18, 64, v18
	v_cmp_lt_i32_e32 vcc, v17, v18
	s_mov_b64 s[10:11], 0
	s_nop 0
	v_cndmask_b32_e32 v17, v217, v17, vcc
	v_lshlrev_b32_e32 v17, 2, v17
	ds_bpermute_b32 v17, v17, v16
	s_waitcnt lgkmcnt(0)
	v_add_f32_e32 v16, v16, v17
	v_xor_b32_e32 v17, 32, v217
	v_cmp_lt_i32_e32 vcc, v17, v18
	s_nop 1
	v_cndmask_b32_e32 v17, v217, v17, vcc
	v_lshlrev_b32_e32 v17, 2, v17
	ds_bpermute_b32 v17, v17, v16
	s_waitcnt lgkmcnt(0)
	v_add_f32_e32 v16, v16, v17
	v_fmamk_f32 v16, v16, 0x3c800000, v212
	v_rsq_f32_e32 v18, v16
	v_lshlrev_b64 v[16:17], 11, v[42:43]
	v_lshl_add_u64 v[16:17], s[36:37], 0, v[16:17]
	v_lshl_add_u64 v[16:17], v[16:17], 0, s[44:45]
	v_pk_mul_f32 v[12:13], v[12:13], v[18:19] op_sel_hi:[1,0]
	v_pk_mul_f32 v[14:15], v[14:15], v[18:19] op_sel_hi:[1,0]
	v_lshl_add_u64 v[16:17], v[16:17], 0, v[156:157]
	v_pk_mul_f32 v[8:9], v[8:9], v[18:19] op_sel_hi:[1,0]
	v_pk_mul_f32 v[10:11], v[10:11], v[18:19] op_sel_hi:[1,0]
	v_pk_mul_f32 v[4:5], v[4:5], v[18:19] op_sel_hi:[1,0]
	v_pk_mul_f32 v[6:7], v[6:7], v[18:19] op_sel_hi:[1,0]
	v_pk_mul_f32 v[0:1], v[0:1], v[18:19] op_sel_hi:[1,0]
	v_pk_mul_f32 v[2:3], v[2:3], v[18:19] op_sel_hi:[1,0]
	s_waitcnt vmcnt(0)
	v_pk_mul_f32 v[12:13], v[20:21], v[12:13]
	v_pk_mul_f32 v[14:15], v[22:23], v[14:15]
	v_cvt_pk_bf16_f32 v12, v12, v13
	v_cvt_pk_bf16_f32 v13, v14, v15
	global_store_dwordx2 v[16:17], v[12:13], off
	global_load_dwordx4 v[12:15], v[40:41], off offset:64
	s_waitcnt vmcnt(0)
	v_pk_mul_f32 v[8:9], v[12:13], v[8:9]
	v_pk_mul_f32 v[10:11], v[14:15], v[10:11]
	v_cvt_pk_bf16_f32 v8, v8, v9
	v_cvt_pk_bf16_f32 v9, v10, v11
	global_store_dwordx2 v[16:17], v[8:9], off offset:32
	global_load_dwordx4 v[8:11], v[40:41], off offset:128
	s_waitcnt vmcnt(0)
	v_pk_mul_f32 v[4:5], v[4:5], v[8:9]
	v_pk_mul_f32 v[6:7], v[6:7], v[10:11]
	v_cvt_pk_bf16_f32 v4, v4, v5
	v_cvt_pk_bf16_f32 v5, v6, v7
	global_store_dwordx2 v[16:17], v[4:5], off offset:64
	global_load_dwordx4 v[4:7], v[40:41], off offset:192
	s_waitcnt vmcnt(0)
	v_pk_mul_f32 v[0:1], v[0:1], v[4:5]
	v_pk_mul_f32 v[2:3], v[2:3], v[6:7]
	v_cvt_pk_bf16_f32 v0, v0, v1
	v_cvt_pk_bf16_f32 v1, v2, v3
	global_store_dwordx2 v[16:17], v[0:1], off offset:96
	s_branch .LBB0_837
